# M2: T2-table fill, AGGW stream fill and carry folds keep 4-8 loads in flight instead of one
# baseline (speedup 1.0000x reference)
.LBB0_565:
	s_waitcnt vmcnt(0)
	v_lshlrev_b32_e32 v2, 4, v0
	v_add_u32_e32 v3, 0x2000, v2
	v_add_u32_e32 v5, 0x4000, v2
	v_add_u32_e32 v6, 0x6000, v2
	global_load_dwordx4 v[220:223], v2, s[12:13]
	global_load_dwordx4 v[224:227], v3, s[12:13]
	global_load_dwordx4 v[238:241], v5, s[12:13]
	global_load_dwordx4 v[242:245], v6, s[12:13]
	s_cmp_lt_i32 s44, 0x1000
	s_cbranch_scc1 .Lmy_stream_tail
	s_add_u32 s14, s12, 0x8000
	s_addc_u32 s15, s13, 0
	s_waitcnt vmcnt(3)
	ds_write_b128 v4, v[220:223]
	global_load_dwordx4 v[220:223], v2, s[14:15]
	s_waitcnt vmcnt(3)
	ds_write_b128 v4, v[224:227] offset:8192
	global_load_dwordx4 v[224:227], v3, s[14:15]
	s_waitcnt vmcnt(3)
	ds_write_b128 v4, v[238:241] offset:16384
	global_load_dwordx4 v[238:241], v5, s[14:15]
	s_waitcnt vmcnt(3)
	ds_write_b128 v4, v[242:245] offset:24576
	global_load_dwordx4 v[242:245], v6, s[14:15]
	v_add_u32_e32 v4, 0x8000, v4
.Lmy_stream_tail:
	s_waitcnt vmcnt(3)
	ds_write_b128 v4, v[220:223]
	s_waitcnt vmcnt(2)
	ds_write_b128 v4, v[224:227] offset:8192
	s_waitcnt vmcnt(1)
	ds_write_b128 v4, v[238:241] offset:16384
	s_waitcnt vmcnt(0)
	ds_write_b128 v4, v[242:245] offset:24576
.LBB0_566:
	s_or_b64 exec, exec, s[0:1]
	v_and_b32_e32 v210, 63, v0
	v_cmp_gt_i32_e32 vcc, s51, v0
	s_waitcnt lgkmcnt(0)
	s_barrier
	s_and_saveexec_b64 s[0:1], vcc
	s_cbranch_execz .LBB0_579
	s_lshl_b32 s5, s40, 12
	s_lshl_b32 s4, s40, 13
	s_addk_i32 s5, 0x2000
	s_and_b64 s[10:11], s[10:11], exec
	s_cselect_b32 s4, s4, s5
	s_sub_i32 s4, s38, s4
	s_ashr_i32 s12, s4, 7
	v_cmp_lt_u32_e32 vcc, 63, v0
	s_and_saveexec_b64 s[10:11], vcc
	s_xor_b64 s[10:11], exec, s[10:11]
	s_cbranch_execz .LBB0_573
	s_cmp_le_i32 s39, s12
	s_cbranch_scc1 .LBB0_573
	s_lshl_b32 s4, s39, 10
	s_add_i32 s4, s4, 0
	s_add_i32 s4, s4, 0x12e00
	v_lshlrev_b32_e32 v3, 2, v210
	v_lshl_add_u32 v2, v210, 3, s4
	v_lshl_or_b32 v3, s39, 9, v3
	s_lshl_b32 s4, s12, 9
	v_subrev_u32_e32 v3, s4, v3
	v_readlane_b32 s4, v255, 23
	s_add_i32 s13, s12, 8
	v_mov_b32_e32 v4, 0
	v_add_u32_e32 v3, s4, v3
	v_add_u32_e32 v2, 0xffffe400, v2
	s_sub_i32 s13, s39, s12
	s_lshr_b32 s13, s13, 3
.Lmy_foldb_loop:
	ds_read_b64 v[220:221], v2 offset:7168
	ds_read_b64 v[222:223], v2 offset:6144
	ds_read_b64 v[224:225], v2 offset:5120
	ds_read_b64 v[226:227], v2 offset:4096
	ds_read_b64 v[238:239], v2 offset:3072
	ds_read_b64 v[240:241], v2 offset:2048
	ds_read_b64 v[242:243], v2 offset:1024
	ds_read_b64 v[244:245], v2
	v_add_u32_e32 v2, 0xffffe000, v2
	s_add_i32 s13, s13, -1
	s_cmp_eq_u32 s13, 0
	s_cbranch_scc1 .Lmy_foldb_last
	s_waitcnt lgkmcnt(0)
	v_fmac_f32_e32 v221, v4, v220
	v_fmac_f32_e32 v223, v221, v222
	v_fmac_f32_e32 v225, v223, v224
	v_fmac_f32_e32 v227, v225, v226
	v_fmac_f32_e32 v239, v227, v238
	v_fmac_f32_e32 v241, v239, v240
	v_fmac_f32_e32 v243, v241, v242
	v_fmac_f32_e32 v245, v243, v244
	v_mov_b32_e32 v4, v245
	v_add_u32_e32 v3, 0xfffff000, v3
	s_branch .Lmy_foldb_loop
.Lmy_foldb_last:
	v_add_u32_e32 v3, 0xfffff200, v3
	s_waitcnt lgkmcnt(0)
	ds_write_b32 v3, v4 offset:3584
	v_fmac_f32_e32 v221, v4, v220
	ds_write_b32 v3, v221 offset:3072
	v_fmac_f32_e32 v223, v221, v222
	ds_write_b32 v3, v223 offset:2560
	v_fmac_f32_e32 v225, v223, v224
	ds_write_b32 v3, v225 offset:2048
	v_fmac_f32_e32 v227, v225, v226
	ds_write_b32 v3, v227 offset:1536
	v_fmac_f32_e32 v239, v227, v238
	ds_write_b32 v3, v239 offset:1024
	v_fmac_f32_e32 v241, v239, v240
	ds_write_b32 v3, v241 offset:512
	v_fmac_f32_e32 v243, v241, v242
	ds_write_b32 v3, v243
	s_mov_b32 s39, s12
.LBB0_573:
	s_andn2_saveexec_b64 s[10:11], s[10:11]
	s_cbranch_execz .LBB0_579
	s_cmp_lt_i32 s12, 0
	s_cbranch_scc1 .LBB0_579
	v_lshlrev_b32_e32 v2, 2, v0
	s_lshl_b32 s4, s12, 9
	v_subrev_u32_e32 v2, s4, v2
	s_add_i32 s4, 0, 0xe000
	v_add_u32_e32 v2, s4, v2
	v_readlane_b32 s4, v255, 22
	s_add_i32 s10, s12, 8
	s_mov_b32 s11, 0
	v_lshl_add_u32 v3, v0, 3, s4
	v_mov_b32_e32 v4, 0
	s_lshr_b32 s11, s10, 3
.Lmy_foldf_loop:
	ds_read_b64 v[220:221], v3
	ds_read_b64 v[222:223], v3 offset:1024
	ds_read_b64 v[224:225], v3 offset:2048
	ds_read_b64 v[226:227], v3 offset:3072
	ds_read_b64 v[238:239], v3 offset:4096
	ds_read_b64 v[240:241], v3 offset:5120
	ds_read_b64 v[242:243], v3 offset:6144
	ds_read_b64 v[244:245], v3 offset:7168
	v_add_u32_e32 v3, 0x2000, v3
	s_add_i32 s11, s11, -1
	s_cmp_eq_u32 s11, 0
	s_cbranch_scc1 .Lmy_foldf_last
	s_waitcnt lgkmcnt(0)
	v_fmac_f32_e32 v221, v4, v220
	v_fmac_f32_e32 v223, v221, v222
	v_fmac_f32_e32 v225, v223, v224
	v_fmac_f32_e32 v227, v225, v226
	v_fmac_f32_e32 v239, v227, v238
	v_fmac_f32_e32 v241, v239, v240
	v_fmac_f32_e32 v243, v241, v242
	v_fmac_f32_e32 v245, v243, v244
	v_mov_b32_e32 v4, v245
	s_branch .Lmy_foldf_loop
.Lmy_foldf_last:
	v_lshlrev_b32_e32 v2, 2, v0
	v_add_u32_e32 v2, 0xe000, v2
	s_waitcnt lgkmcnt(0)
	ds_write_b32 v2, v4
	v_fmac_f32_e32 v221, v4, v220
	ds_write_b32 v2, v221 offset:512
	v_fmac_f32_e32 v223, v221, v222
	ds_write_b32 v2, v223 offset:1024
	v_fmac_f32_e32 v225, v223, v224
	ds_write_b32 v2, v225 offset:1536
	v_fmac_f32_e32 v227, v225, v226
	ds_write_b32 v2, v227 offset:2048
	v_fmac_f32_e32 v239, v227, v238
	ds_write_b32 v2, v239 offset:2560
	v_fmac_f32_e32 v241, v239, v240
	ds_write_b32 v2, v241 offset:3072
	v_fmac_f32_e32 v243, v241, v242
	ds_write_b32 v2, v243 offset:3584
	s_mov_b32 s11, s10

.LBB0_585:
	s_waitcnt vmcnt(0)
	v_lshlrev_b32_e32 v4, 4, v0
	v_add_u32_e32 v5, 0x2000, v4
	v_add_u32_e32 v6, 0x4000, v4
	v_add_u32_e32 v7, 0x6000, v4
	v_add_u32_e32 v8, 0x8000, v4
	v_add_u32_e32 v9, 0xa000, v4
	v_add_u32_e32 v10, 0xc000, v4
	v_add_u32_e32 v11, 0xe000, v4
	global_load_dwordx4 v[220:223], v4, s[70:71]
	global_load_dwordx4 v[224:227], v5, s[70:71]
	global_load_dwordx4 v[238:241], v6, s[70:71]
	global_load_dwordx4 v[242:245], v7, s[70:71]
	v_lshrrev_b32_e32 v2, 4, v0
	v_mul_u32_u24_e32 v2, 0x110, v2
	v_and_b32_e32 v3, 15, v0
	v_lshl_add_u32 v2, v3, 4, v2
	v_add_u32_e32 v3, v234, v2
	v_add_u32_e32 v2, v235, v2
	s_waitcnt vmcnt(3)
	ds_write_b128 v2, v[220:223]
	global_load_dwordx4 v[220:223], v8, s[70:71]
	s_waitcnt vmcnt(3)
	ds_write_b128 v2, v[224:227] offset:8704
	global_load_dwordx4 v[224:227], v9, s[70:71]
	s_waitcnt vmcnt(3)
	ds_write_b128 v2, v[238:241] offset:17408
	global_load_dwordx4 v[238:241], v10, s[70:71]
	s_waitcnt vmcnt(3)
	ds_write_b128 v2, v[242:245] offset:26112
	global_load_dwordx4 v[242:245], v11, s[70:71]
	s_waitcnt vmcnt(3)
	ds_write_b128 v3, v[220:223]
	s_waitcnt vmcnt(2)
	ds_write_b128 v3, v[224:227] offset:8704
	s_waitcnt vmcnt(1)
	ds_write_b128 v3, v[238:241] offset:17408
	s_waitcnt vmcnt(0)
	ds_write_b128 v3, v[242:245] offset:26112
	s_or_b64 exec, exec, s[10:11]
